# out-GEMM epilogue: g hoisted, residual loads 2 rows deep, xg packed in place; on top of merge+gates epilogues
# baseline (speedup 1.0000x reference)
; __device__ __forceinline__ u32x4 pack8(f32x4 v0, f32x4 v1) { u32x4 w; w.x = cvt_pk_bf16(v0[0], v0[1]); w.y = cvt_pk_bf16(v0[2], v0[3]); w.z = cvt_pk_bf16(v1[0], v1[1]); w.w = cvt_pk_bf16(v1[2], v1[3]); return w; }
;     __device__ __forceinline__ void operator()(f32x4 (&acc)[2][2][4][2], const Unit& u, int wr, int wc, int fr, int fq) const {
;         const int row0 = u.pm * BM + wr * 64 + fr; const int colt = u.pn * BM + wc * 32 + 8 * fq;
; #pragma unroll
;         for (int ai = 0; ai < 2; ++ai)
; #pragma unroll
;             for (int m = 0; m < 4; ++m) { const int row = row0 + ai * HALF + m * 16; float ss = 0.f;
; #pragma unroll
;                 for (int bj = 0; bj < 2; ++bj) { const int col = colt + bj * HALF; const size_t off = (size_t)row * DM + col;
;                     const f32x4 x0 = *(const f32x4*)(in + off) + acc[ai][bj][m][0], x1 = *(const f32x4*)(in + off + 4) + acc[ai][bj][m][1];
;                     *(f32x4*)(out + off) = x0; *(f32x4*)(out + off + 4) = x1;
;                     const f32x4 g0 = *(const f32x4*)(g + col), g1 = *(const f32x4*)(g + col + 4);
;                     *(u32x4*)(xg + off) = pack8(x0 * g0, x1 * g1);
;                     ss += (x0[0] * x0[0] + x0[1] * x0[1]) + (x0[2] * x0[2] + x0[3] * x0[3]) + (x1[0] * x1[0] + x1[1] * x1[1]) + (x1[2] * x1[2] + x1[3] * x1[3]); }
;                 ss += __shfl_xor(ss, 16); ss += __shfl_xor(ss, 32);
;                 if (fq == 0) atomicAdd(sumsq + row, ss);
;                 if (m == 3) asm volatile("" ::: "memory"); }
.LBB0_1054:
	v_lshl_add_u32 v146, s28, 8, v1
	v_lshl_or_b32 v144, s30, 8, v149
	v_lshl_add_u32 v147, v146, 10, v144
	v_lshlrev_b32_e32 v142, 2, v147
	v_lshlrev_b32_e32 v143, 1, v147
	v_lshlrev_b32_e32 v145, 2, v144
	v_lshlrev_b32_e32 v146, 2, v146
	global_load_dwordx4 v[152:155], v145, s[14:15]
	global_load_dwordx4 v[156:159], v145, s[14:15] offset:16
	global_load_dwordx4 v[160:163], v145, s[14:15] offset:512
	global_load_dwordx4 v[164:167], v145, s[14:15] offset:528
	s_mov_b64 vcc, s[4:5]
	global_load_dwordx4 v[168:171], v142, vcc
	global_load_dwordx4 v[172:175], v142, vcc offset:16
	global_load_dwordx4 v[176:179], v142, vcc offset:512
	global_load_dwordx4 v[182:185], v142, vcc offset:528
	s_add_u32 vcc_lo, s4, 0x10000
	s_addc_u32 vcc_hi, s5, 0
	global_load_dwordx4 v[186:189], v142, vcc
	global_load_dwordx4 v[190:193], v142, vcc offset:16
	global_load_dwordx4 v[194:197], v142, vcc offset:512
	global_load_dwordx4 v[198:201], v142, vcc offset:528
	s_waitcnt vmcnt(4)
	v_pk_add_f32 v[126:127], v[126:127], v[168:169]
	v_pk_add_f32 v[128:129], v[128:129], v[170:171]
	v_pk_add_f32 v[122:123], v[122:123], v[172:173]
	v_pk_add_f32 v[124:125], v[124:125], v[174:175]
	v_pk_add_f32 v[118:119], v[118:119], v[176:177]
	v_pk_add_f32 v[120:121], v[120:121], v[178:179]
	v_pk_add_f32 v[114:115], v[114:115], v[182:183]
	v_pk_add_f32 v[116:117], v[116:117], v[184:185]
	s_mov_b64 vcc, s[2:3]
	global_store_dwordx4 v142, v[126:129], vcc
	global_store_dwordx4 v142, v[122:125], vcc offset:16
	global_store_dwordx4 v142, v[118:121], vcc offset:512
	global_store_dwordx4 v142, v[114:117], vcc offset:528
	s_add_u32 vcc_lo, s4, 0x20000
	s_addc_u32 vcc_hi, s5, 0
	global_load_dwordx4 v[168:171], v142, vcc
	global_load_dwordx4 v[172:175], v142, vcc offset:16
	global_load_dwordx4 v[176:179], v142, vcc offset:512
	global_load_dwordx4 v[182:185], v142, vcc offset:528
	v_mul_f32_e32 v202, v126, v126
	v_fmac_f32_e32 v202, v127, v127
	v_fmac_f32_e32 v202, v128, v128
	v_fmac_f32_e32 v202, v129, v129
	v_mul_f32_e32 v203, v122, v122
	v_fmac_f32_e32 v203, v123, v123
	v_fmac_f32_e32 v203, v124, v124
	v_fmac_f32_e32 v203, v125, v125
	v_mul_f32_e32 v204, v118, v118
	v_fmac_f32_e32 v204, v119, v119
	v_fmac_f32_e32 v204, v120, v120
	v_fmac_f32_e32 v204, v121, v121
	v_mul_f32_e32 v205, v114, v114
	v_fmac_f32_e32 v205, v115, v115
	v_fmac_f32_e32 v205, v116, v116
	v_fmac_f32_e32 v205, v117, v117
	v_add_f32_e32 v202, v202, v203
	v_add_f32_e32 v204, v204, v205
	v_add_f32_e32 v202, v202, v204
	ds_bpermute_b32 v206, v253, v202
	s_mov_b64 vcc, s[12:13]
	v_pk_mul_f32 v[126:127], v[126:127], v[152:153]
	v_pk_mul_f32 v[128:129], v[128:129], v[154:155]
	v_pk_mul_f32 v[122:123], v[122:123], v[156:157]
	v_pk_mul_f32 v[124:125], v[124:125], v[158:159]
	v_cvt_pk_bf16_f32 v126, v126, v127
	v_cvt_pk_bf16_f32 v127, v128, v129
	v_cvt_pk_bf16_f32 v128, v122, v123
	v_cvt_pk_bf16_f32 v129, v124, v125
	global_store_dwordx4 v143, v[126:129], vcc
	v_pk_mul_f32 v[118:119], v[118:119], v[160:161]
	v_pk_mul_f32 v[120:121], v[120:121], v[162:163]
	v_pk_mul_f32 v[114:115], v[114:115], v[164:165]
	v_pk_mul_f32 v[116:117], v[116:117], v[166:167]
	v_cvt_pk_bf16_f32 v118, v118, v119
	v_cvt_pk_bf16_f32 v119, v120, v121
	v_cvt_pk_bf16_f32 v120, v114, v115
	v_cvt_pk_bf16_f32 v121, v116, v117
	global_store_dwordx4 v143, v[118:121], vcc offset:256
	s_waitcnt lgkmcnt(0)
	v_add_f32_e32 v202, v202, v206
	ds_bpermute_b32 v206, v230, v202
	s_waitcnt lgkmcnt(0)
	v_add_f32_e32 v202, v202, v206
	s_and_saveexec_b64 s[28:29], s[6:7]
	global_atomic_add_f32 v146, v202, s[16:17]
	s_or_b64 exec, exec, s[28:29]
	s_waitcnt vmcnt(11)
	v_pk_add_f32 v[110:111], v[110:111], v[186:187]
	v_pk_add_f32 v[112:113], v[112:113], v[188:189]
	v_pk_add_f32 v[106:107], v[106:107], v[190:191]
	v_pk_add_f32 v[108:109], v[108:109], v[192:193]
	v_pk_add_f32 v[102:103], v[102:103], v[194:195]
	v_pk_add_f32 v[104:105], v[104:105], v[196:197]
	v_pk_add_f32 v[98:99], v[98:99], v[198:199]
	v_pk_add_f32 v[100:101], v[100:101], v[200:201]
	s_add_u32 vcc_lo, s2, 0x10000
	s_addc_u32 vcc_hi, s3, 0
	global_store_dwordx4 v142, v[110:113], vcc
	global_store_dwordx4 v142, v[106:109], vcc offset:16
	global_store_dwordx4 v142, v[102:105], vcc offset:512
	global_store_dwordx4 v142, v[98:101], vcc offset:528
	s_add_u32 vcc_lo, s4, 0x30000
	s_addc_u32 vcc_hi, s5, 0
	global_load_dwordx4 v[186:189], v142, vcc
	global_load_dwordx4 v[190:193], v142, vcc offset:16
	global_load_dwordx4 v[194:197], v142, vcc offset:512
	global_load_dwordx4 v[198:201], v142, vcc offset:528
	v_mul_f32_e32 v202, v110, v110
	v_fmac_f32_e32 v202, v111, v111
	v_fmac_f32_e32 v202, v112, v112
	v_fmac_f32_e32 v202, v113, v113
	v_mul_f32_e32 v203, v106, v106
	v_fmac_f32_e32 v203, v107, v107
	v_fmac_f32_e32 v203, v108, v108
	v_fmac_f32_e32 v203, v109, v109
	v_mul_f32_e32 v204, v102, v102
	v_fmac_f32_e32 v204, v103, v103
	v_fmac_f32_e32 v204, v104, v104
	v_fmac_f32_e32 v204, v105, v105
	v_mul_f32_e32 v205, v98, v98
	v_fmac_f32_e32 v205, v99, v99
	v_fmac_f32_e32 v205, v100, v100
	v_fmac_f32_e32 v205, v101, v101
	v_add_f32_e32 v202, v202, v203
	v_add_f32_e32 v204, v204, v205
	v_add_f32_e32 v202, v202, v204
	ds_bpermute_b32 v206, v253, v202
	s_add_u32 vcc_lo, s12, 0x8000
	s_addc_u32 vcc_hi, s13, 0
	v_pk_mul_f32 v[110:111], v[110:111], v[152:153]
	v_pk_mul_f32 v[112:113], v[112:113], v[154:155]
	v_pk_mul_f32 v[106:107], v[106:107], v[156:157]
	v_pk_mul_f32 v[108:109], v[108:109], v[158:159]
	v_cvt_pk_bf16_f32 v110, v110, v111
	v_cvt_pk_bf16_f32 v111, v112, v113
	v_cvt_pk_bf16_f32 v112, v106, v107
	v_cvt_pk_bf16_f32 v113, v108, v109
	global_store_dwordx4 v143, v[110:113], vcc
	v_pk_mul_f32 v[102:103], v[102:103], v[160:161]
	v_pk_mul_f32 v[104:105], v[104:105], v[162:163]
	v_pk_mul_f32 v[98:99], v[98:99], v[164:165]
	v_pk_mul_f32 v[100:101], v[100:101], v[166:167]
	v_cvt_pk_bf16_f32 v102, v102, v103
	v_cvt_pk_bf16_f32 v103, v104, v105
	v_cvt_pk_bf16_f32 v104, v98, v99
	v_cvt_pk_bf16_f32 v105, v100, v101
	global_store_dwordx4 v143, v[102:105], vcc offset:256
	s_waitcnt lgkmcnt(0)
; __device__ __forceinline__ u32x4 pack8(f32x4 v0, f32x4 v1) { u32x4 w; w.x = cvt_pk_bf16(v0[0], v0[1]); w.y = cvt_pk_bf16(v0[2], v0[3]); w.z = cvt_pk_bf16(v1[0], v1[1]); w.w = cvt_pk_bf16(v1[2], v1[3]); return w; }
;     __device__ __forceinline__ void operator()(f32x4 (&acc)[2][2][4][2], const Unit& u, int wr, int wc, int fr, int fq) const {
;         const int row0 = u.pm * BM + wr * 64 + fr; const int colt = u.pn * BM + wc * 32 + 8 * fq;
; #pragma unroll
;         for (int ai = 0; ai < 2; ++ai)
; #pragma unroll
;             for (int m = 0; m < 4; ++m) { const int row = row0 + ai * HALF + m * 16; float ss = 0.f;
; #pragma unroll
;                 for (int bj = 0; bj < 2; ++bj) { const int col = colt + bj * HALF; const size_t off = (size_t)row * DM + col;
;                     const f32x4 x0 = *(const f32x4*)(in + off) + acc[ai][bj][m][0], x1 = *(const f32x4*)(in + off + 4) + acc[ai][bj][m][1];
;                     *(f32x4*)(out + off) = x0; *(f32x4*)(out + off + 4) = x1;
;                     const f32x4 g0 = *(const f32x4*)(g + col), g1 = *(const f32x4*)(g + col + 4);
;                     *(u32x4*)(xg + off) = pack8(x0 * g0, x1 * g1);
;                     ss += (x0[0] * x0[0] + x0[1] * x0[1]) + (x0[2] * x0[2] + x0[3] * x0[3]) + (x1[0] * x1[0] + x1[1] * x1[1]) + (x1[2] * x1[2] + x1[3] * x1[3]); }
;                 ss += __shfl_xor(ss, 16); ss += __shfl_xor(ss, 32);
;                 if (fq == 0) atomicAdd(sumsq + row, ss);
;                 if (m == 3) asm volatile("" ::: "memory"); }
	v_add_f32_e32 v202, v202, v206
	ds_bpermute_b32 v206, v230, v202
	s_waitcnt lgkmcnt(0)
	v_add_f32_e32 v202, v202, v206
	s_and_saveexec_b64 s[28:29], s[6:7]
	global_atomic_add_f32 v146, v202, s[16:17] offset:64
	s_or_b64 exec, exec, s[28:29]
	s_waitcnt vmcnt(14)
	v_pk_add_f32 v[94:95], v[94:95], v[168:169]
	v_pk_add_f32 v[96:97], v[96:97], v[170:171]
	v_pk_add_f32 v[90:91], v[90:91], v[172:173]
	v_pk_add_f32 v[92:93], v[92:93], v[174:175]
	v_pk_add_f32 v[86:87], v[86:87], v[176:177]
	v_pk_add_f32 v[88:89], v[88:89], v[178:179]
	v_pk_add_f32 v[82:83], v[82:83], v[182:183]
	v_pk_add_f32 v[84:85], v[84:85], v[184:185]
	s_add_u32 vcc_lo, s2, 0x20000
	s_addc_u32 vcc_hi, s3, 0
	global_store_dwordx4 v142, v[94:97], vcc
	global_store_dwordx4 v142, v[90:93], vcc offset:16
	global_store_dwordx4 v142, v[86:89], vcc offset:512
	global_store_dwordx4 v142, v[82:85], vcc offset:528
	s_add_u32 vcc_lo, s4, 0x80000
	s_addc_u32 vcc_hi, s5, 0
	global_load_dwordx4 v[168:171], v142, vcc
	global_load_dwordx4 v[172:175], v142, vcc offset:16
	global_load_dwordx4 v[176:179], v142, vcc offset:512
	global_load_dwordx4 v[182:185], v142, vcc offset:528
	v_mul_f32_e32 v202, v94, v94
	v_fmac_f32_e32 v202, v95, v95
	v_fmac_f32_e32 v202, v96, v96
	v_fmac_f32_e32 v202, v97, v97
	v_mul_f32_e32 v203, v90, v90
	v_fmac_f32_e32 v203, v91, v91
	v_fmac_f32_e32 v203, v92, v92
	v_fmac_f32_e32 v203, v93, v93
	v_mul_f32_e32 v204, v86, v86
	v_fmac_f32_e32 v204, v87, v87
	v_fmac_f32_e32 v204, v88, v88
	v_fmac_f32_e32 v204, v89, v89
	v_mul_f32_e32 v205, v82, v82
	v_fmac_f32_e32 v205, v83, v83
	v_fmac_f32_e32 v205, v84, v84
	v_fmac_f32_e32 v205, v85, v85
	v_add_f32_e32 v202, v202, v203
	v_add_f32_e32 v204, v204, v205
	v_add_f32_e32 v202, v202, v204
	ds_bpermute_b32 v206, v253, v202
	s_add_u32 vcc_lo, s12, 0x10000
	s_addc_u32 vcc_hi, s13, 0
	v_pk_mul_f32 v[94:95], v[94:95], v[152:153]
	v_pk_mul_f32 v[96:97], v[96:97], v[154:155]
	v_pk_mul_f32 v[90:91], v[90:91], v[156:157]
	v_pk_mul_f32 v[92:93], v[92:93], v[158:159]
	v_cvt_pk_bf16_f32 v94, v94, v95
	v_cvt_pk_bf16_f32 v95, v96, v97
	v_cvt_pk_bf16_f32 v96, v90, v91
	v_cvt_pk_bf16_f32 v97, v92, v93
	global_store_dwordx4 v143, v[94:97], vcc
	v_pk_mul_f32 v[86:87], v[86:87], v[160:161]
	v_pk_mul_f32 v[88:89], v[88:89], v[162:163]
	v_pk_mul_f32 v[82:83], v[82:83], v[164:165]
	v_pk_mul_f32 v[84:85], v[84:85], v[166:167]
	v_cvt_pk_bf16_f32 v86, v86, v87
	v_cvt_pk_bf16_f32 v87, v88, v89
	v_cvt_pk_bf16_f32 v88, v82, v83
	v_cvt_pk_bf16_f32 v89, v84, v85
	global_store_dwordx4 v143, v[86:89], vcc offset:256
	s_waitcnt lgkmcnt(0)
	v_add_f32_e32 v202, v202, v206
	ds_bpermute_b32 v206, v230, v202
	s_waitcnt lgkmcnt(0)
	v_add_f32_e32 v202, v202, v206
	s_and_saveexec_b64 s[28:29], s[6:7]
	global_atomic_add_f32 v146, v202, s[16:17] offset:128
	s_or_b64 exec, exec, s[28:29]
	s_waitcnt vmcnt(14)
	v_pk_add_f32 v[78:79], v[78:79], v[186:187]
	v_pk_add_f32 v[80:81], v[80:81], v[188:189]
	v_pk_add_f32 v[74:75], v[74:75], v[190:191]
	v_pk_add_f32 v[76:77], v[76:77], v[192:193]
	v_pk_add_f32 v[70:71], v[70:71], v[194:195]
	v_pk_add_f32 v[72:73], v[72:73], v[196:197]
	v_pk_add_f32 v[66:67], v[66:67], v[198:199]
	v_pk_add_f32 v[68:69], v[68:69], v[200:201]
	s_add_u32 vcc_lo, s2, 0x30000
	s_addc_u32 vcc_hi, s3, 0
	global_store_dwordx4 v142, v[78:81], vcc
	global_store_dwordx4 v142, v[74:77], vcc offset:16
	global_store_dwordx4 v142, v[70:73], vcc offset:512
	global_store_dwordx4 v142, v[66:69], vcc offset:528
	s_add_u32 vcc_lo, s4, 0x90000
	s_addc_u32 vcc_hi, s5, 0
	global_load_dwordx4 v[186:189], v142, vcc
	global_load_dwordx4 v[190:193], v142, vcc offset:16
	global_load_dwordx4 v[194:197], v142, vcc offset:512
	global_load_dwordx4 v[198:201], v142, vcc offset:528
	v_mul_f32_e32 v202, v78, v78
	v_fmac_f32_e32 v202, v79, v79
	v_fmac_f32_e32 v202, v80, v80
	v_fmac_f32_e32 v202, v81, v81
	v_mul_f32_e32 v203, v74, v74
	v_fmac_f32_e32 v203, v75, v75
	v_fmac_f32_e32 v203, v76, v76
	v_fmac_f32_e32 v203, v77, v77
	v_mul_f32_e32 v204, v70, v70
	v_fmac_f32_e32 v204, v71, v71
	v_fmac_f32_e32 v204, v72, v72
	v_fmac_f32_e32 v204, v73, v73
	v_mul_f32_e32 v205, v66, v66
	v_fmac_f32_e32 v205, v67, v67
	v_fmac_f32_e32 v205, v68, v68
	v_fmac_f32_e32 v205, v69, v69
	v_add_f32_e32 v202, v202, v203
	v_add_f32_e32 v204, v204, v205
	v_add_f32_e32 v202, v202, v204
	ds_bpermute_b32 v206, v253, v202
	s_add_u32 vcc_lo, s12, 0x18000
	s_addc_u32 vcc_hi, s13, 0
	v_pk_mul_f32 v[78:79], v[78:79], v[152:153]
	v_pk_mul_f32 v[80:81], v[80:81], v[154:155]
	v_pk_mul_f32 v[74:75], v[74:75], v[156:157]
	v_pk_mul_f32 v[76:77], v[76:77], v[158:159]
	v_cvt_pk_bf16_f32 v78, v78, v79
	v_cvt_pk_bf16_f32 v79, v80, v81
	v_cvt_pk_bf16_f32 v80, v74, v75
	v_cvt_pk_bf16_f32 v81, v76, v77
	global_store_dwordx4 v143, v[78:81], vcc
	v_pk_mul_f32 v[70:71], v[70:71], v[160:161]
	v_pk_mul_f32 v[72:73], v[72:73], v[162:163]
	v_pk_mul_f32 v[66:67], v[66:67], v[164:165]
	v_pk_mul_f32 v[68:69], v[68:69], v[166:167]
	v_cvt_pk_bf16_f32 v70, v70, v71
	v_cvt_pk_bf16_f32 v71, v72, v73
	v_cvt_pk_bf16_f32 v72, v66, v67
	v_cvt_pk_bf16_f32 v73, v68, v69
	global_store_dwordx4 v143, v[70:73], vcc offset:256
	s_waitcnt lgkmcnt(0)
	v_add_f32_e32 v202, v202, v206
	ds_bpermute_b32 v206, v230, v202
	s_waitcnt lgkmcnt(0)
	v_add_f32_e32 v202, v202, v206
	s_and_saveexec_b64 s[28:29], s[6:7]
	global_atomic_add_f32 v146, v202, s[16:17] offset:192
	s_or_b64 exec, exec, s[28:29]
	s_waitcnt vmcnt(14)
; __device__ __forceinline__ u32x4 pack8(f32x4 v0, f32x4 v1) { u32x4 w; w.x = cvt_pk_bf16(v0[0], v0[1]); w.y = cvt_pk_bf16(v0[2], v0[3]); w.z = cvt_pk_bf16(v1[0], v1[1]); w.w = cvt_pk_bf16(v1[2], v1[3]); return w; }
;     __device__ __forceinline__ void operator()(f32x4 (&acc)[2][2][4][2], const Unit& u, int wr, int wc, int fr, int fq) const {
;         const int row0 = u.pm * BM + wr * 64 + fr; const int colt = u.pn * BM + wc * 32 + 8 * fq;
; #pragma unroll
;         for (int ai = 0; ai < 2; ++ai)
; #pragma unroll
;             for (int m = 0; m < 4; ++m) { const int row = row0 + ai * HALF + m * 16; float ss = 0.f;
; #pragma unroll
;                 for (int bj = 0; bj < 2; ++bj) { const int col = colt + bj * HALF; const size_t off = (size_t)row * DM + col;
;                     const f32x4 x0 = *(const f32x4*)(in + off) + acc[ai][bj][m][0], x1 = *(const f32x4*)(in + off + 4) + acc[ai][bj][m][1];
;                     *(f32x4*)(out + off) = x0; *(f32x4*)(out + off + 4) = x1;
;                     const f32x4 g0 = *(const f32x4*)(g + col), g1 = *(const f32x4*)(g + col + 4);
;                     *(u32x4*)(xg + off) = pack8(x0 * g0, x1 * g1);
;                     ss += (x0[0] * x0[0] + x0[1] * x0[1]) + (x0[2] * x0[2] + x0[3] * x0[3]) + (x1[0] * x1[0] + x1[1] * x1[1]) + (x1[2] * x1[2] + x1[3] * x1[3]); }
;                 ss += __shfl_xor(ss, 16); ss += __shfl_xor(ss, 32);
;                 if (fq == 0) atomicAdd(sumsq + row, ss);
;                 if (m == 3) asm volatile("" ::: "memory"); }
	v_pk_add_f32 v[62:63], v[62:63], v[168:169]
	v_pk_add_f32 v[64:65], v[64:65], v[170:171]
	v_pk_add_f32 v[58:59], v[58:59], v[172:173]
	v_pk_add_f32 v[60:61], v[60:61], v[174:175]
	v_pk_add_f32 v[54:55], v[54:55], v[176:177]
	v_pk_add_f32 v[56:57], v[56:57], v[178:179]
	v_pk_add_f32 v[50:51], v[50:51], v[182:183]
	v_pk_add_f32 v[52:53], v[52:53], v[184:185]
	s_add_u32 vcc_lo, s2, 0x80000
	s_addc_u32 vcc_hi, s3, 0
	global_store_dwordx4 v142, v[62:65], vcc
	global_store_dwordx4 v142, v[58:61], vcc offset:16
	global_store_dwordx4 v142, v[54:57], vcc offset:512
	global_store_dwordx4 v142, v[50:53], vcc offset:528
	s_add_u32 vcc_lo, s4, 0xa0000
	s_addc_u32 vcc_hi, s5, 0
	global_load_dwordx4 v[168:171], v142, vcc
	global_load_dwordx4 v[172:175], v142, vcc offset:16
	global_load_dwordx4 v[176:179], v142, vcc offset:512
	global_load_dwordx4 v[182:185], v142, vcc offset:528
	v_mul_f32_e32 v202, v62, v62
	v_fmac_f32_e32 v202, v63, v63
	v_fmac_f32_e32 v202, v64, v64
	v_fmac_f32_e32 v202, v65, v65
	v_mul_f32_e32 v203, v58, v58
	v_fmac_f32_e32 v203, v59, v59
	v_fmac_f32_e32 v203, v60, v60
	v_fmac_f32_e32 v203, v61, v61
	v_mul_f32_e32 v204, v54, v54
	v_fmac_f32_e32 v204, v55, v55
	v_fmac_f32_e32 v204, v56, v56
	v_fmac_f32_e32 v204, v57, v57
	v_mul_f32_e32 v205, v50, v50
	v_fmac_f32_e32 v205, v51, v51
	v_fmac_f32_e32 v205, v52, v52
	v_fmac_f32_e32 v205, v53, v53
	v_add_f32_e32 v202, v202, v203
	v_add_f32_e32 v204, v204, v205
	v_add_f32_e32 v202, v202, v204
	ds_bpermute_b32 v206, v253, v202
	s_add_u32 vcc_lo, s12, 0x40000
	s_addc_u32 vcc_hi, s13, 0
	v_pk_mul_f32 v[62:63], v[62:63], v[152:153]
	v_pk_mul_f32 v[64:65], v[64:65], v[154:155]
	v_pk_mul_f32 v[58:59], v[58:59], v[156:157]
	v_pk_mul_f32 v[60:61], v[60:61], v[158:159]
	v_cvt_pk_bf16_f32 v62, v62, v63
	v_cvt_pk_bf16_f32 v63, v64, v65
	v_cvt_pk_bf16_f32 v64, v58, v59
	v_cvt_pk_bf16_f32 v65, v60, v61
	global_store_dwordx4 v143, v[62:65], vcc
	v_pk_mul_f32 v[54:55], v[54:55], v[160:161]
	v_pk_mul_f32 v[56:57], v[56:57], v[162:163]
	v_pk_mul_f32 v[50:51], v[50:51], v[164:165]
	v_pk_mul_f32 v[52:53], v[52:53], v[166:167]
	v_cvt_pk_bf16_f32 v54, v54, v55
	v_cvt_pk_bf16_f32 v55, v56, v57
	v_cvt_pk_bf16_f32 v56, v50, v51
	v_cvt_pk_bf16_f32 v57, v52, v53
	global_store_dwordx4 v143, v[54:57], vcc offset:256
	s_waitcnt lgkmcnt(0)
	v_add_f32_e32 v202, v202, v206
	ds_bpermute_b32 v206, v230, v202
	s_waitcnt lgkmcnt(0)
	v_add_f32_e32 v202, v202, v206
	s_and_saveexec_b64 s[28:29], s[6:7]
	global_atomic_add_f32 v146, v202, s[16:17] offset:512
	s_or_b64 exec, exec, s[28:29]
	s_waitcnt vmcnt(14)
	v_pk_add_f32 v[46:47], v[46:47], v[186:187]
	v_pk_add_f32 v[48:49], v[48:49], v[188:189]
	v_pk_add_f32 v[42:43], v[42:43], v[190:191]
	v_pk_add_f32 v[44:45], v[44:45], v[192:193]
	v_pk_add_f32 v[38:39], v[38:39], v[194:195]
	v_pk_add_f32 v[40:41], v[40:41], v[196:197]
	v_pk_add_f32 v[34:35], v[34:35], v[198:199]
	v_pk_add_f32 v[36:37], v[36:37], v[200:201]
	s_add_u32 vcc_lo, s2, 0x90000
	s_addc_u32 vcc_hi, s3, 0
	global_store_dwordx4 v142, v[46:49], vcc
	global_store_dwordx4 v142, v[42:45], vcc offset:16
	global_store_dwordx4 v142, v[38:41], vcc offset:512
	global_store_dwordx4 v142, v[34:37], vcc offset:528
	s_add_u32 vcc_lo, s4, 0xb0000
	s_addc_u32 vcc_hi, s5, 0
	global_load_dwordx4 v[186:189], v142, vcc
	global_load_dwordx4 v[190:193], v142, vcc offset:16
	global_load_dwordx4 v[194:197], v142, vcc offset:512
	global_load_dwordx4 v[198:201], v142, vcc offset:528
	v_mul_f32_e32 v202, v46, v46
	v_fmac_f32_e32 v202, v47, v47
	v_fmac_f32_e32 v202, v48, v48
	v_fmac_f32_e32 v202, v49, v49
	v_mul_f32_e32 v203, v42, v42
	v_fmac_f32_e32 v203, v43, v43
	v_fmac_f32_e32 v203, v44, v44
	v_fmac_f32_e32 v203, v45, v45
	v_mul_f32_e32 v204, v38, v38
	v_fmac_f32_e32 v204, v39, v39
	v_fmac_f32_e32 v204, v40, v40
	v_fmac_f32_e32 v204, v41, v41
	v_mul_f32_e32 v205, v34, v34
	v_fmac_f32_e32 v205, v35, v35
	v_fmac_f32_e32 v205, v36, v36
	v_fmac_f32_e32 v205, v37, v37
	v_add_f32_e32 v202, v202, v203
	v_add_f32_e32 v204, v204, v205
	v_add_f32_e32 v202, v202, v204
	ds_bpermute_b32 v206, v253, v202
	s_add_u32 vcc_lo, s12, 0x48000
	s_addc_u32 vcc_hi, s13, 0
	v_pk_mul_f32 v[46:47], v[46:47], v[152:153]
	v_pk_mul_f32 v[48:49], v[48:49], v[154:155]
	v_pk_mul_f32 v[42:43], v[42:43], v[156:157]
	v_pk_mul_f32 v[44:45], v[44:45], v[158:159]
	v_cvt_pk_bf16_f32 v46, v46, v47
	v_cvt_pk_bf16_f32 v47, v48, v49
	v_cvt_pk_bf16_f32 v48, v42, v43
	v_cvt_pk_bf16_f32 v49, v44, v45
	global_store_dwordx4 v143, v[46:49], vcc
	v_pk_mul_f32 v[38:39], v[38:39], v[160:161]
	v_pk_mul_f32 v[40:41], v[40:41], v[162:163]
	v_pk_mul_f32 v[34:35], v[34:35], v[164:165]
	v_pk_mul_f32 v[36:37], v[36:37], v[166:167]
	v_cvt_pk_bf16_f32 v38, v38, v39
	v_cvt_pk_bf16_f32 v39, v40, v41
	v_cvt_pk_bf16_f32 v40, v34, v35
	v_cvt_pk_bf16_f32 v41, v36, v37
	global_store_dwordx4 v143, v[38:41], vcc offset:256
	s_waitcnt lgkmcnt(0)
	v_add_f32_e32 v202, v202, v206
	ds_bpermute_b32 v206, v230, v202
	s_waitcnt lgkmcnt(0)
; __device__ __forceinline__ u32x4 pack8(f32x4 v0, f32x4 v1) { u32x4 w; w.x = cvt_pk_bf16(v0[0], v0[1]); w.y = cvt_pk_bf16(v0[2], v0[3]); w.z = cvt_pk_bf16(v1[0], v1[1]); w.w = cvt_pk_bf16(v1[2], v1[3]); return w; }
;     __device__ __forceinline__ void operator()(f32x4 (&acc)[2][2][4][2], const Unit& u, int wr, int wc, int fr, int fq) const {
;         const int row0 = u.pm * BM + wr * 64 + fr; const int colt = u.pn * BM + wc * 32 + 8 * fq;
; #pragma unroll
;         for (int ai = 0; ai < 2; ++ai)
; #pragma unroll
;             for (int m = 0; m < 4; ++m) { const int row = row0 + ai * HALF + m * 16; float ss = 0.f;
; #pragma unroll
;                 for (int bj = 0; bj < 2; ++bj) { const int col = colt + bj * HALF; const size_t off = (size_t)row * DM + col;
;                     const f32x4 x0 = *(const f32x4*)(in + off) + acc[ai][bj][m][0], x1 = *(const f32x4*)(in + off + 4) + acc[ai][bj][m][1];
;                     *(f32x4*)(out + off) = x0; *(f32x4*)(out + off + 4) = x1;
;                     const f32x4 g0 = *(const f32x4*)(g + col), g1 = *(const f32x4*)(g + col + 4);
;                     *(u32x4*)(xg + off) = pack8(x0 * g0, x1 * g1);
;                     ss += (x0[0] * x0[0] + x0[1] * x0[1]) + (x0[2] * x0[2] + x0[3] * x0[3]) + (x1[0] * x1[0] + x1[1] * x1[1]) + (x1[2] * x1[2] + x1[3] * x1[3]); }
;                 ss += __shfl_xor(ss, 16); ss += __shfl_xor(ss, 32);
;                 if (fq == 0) atomicAdd(sumsq + row, ss);
;                 if (m == 3) asm volatile("" ::: "memory"); }
	v_add_f32_e32 v202, v202, v206
	s_and_saveexec_b64 s[28:29], s[6:7]
	global_atomic_add_f32 v146, v202, s[16:17] offset:576
	s_or_b64 exec, exec, s[28:29]
	s_waitcnt vmcnt(14)
	v_pk_add_f32 v[30:31], v[30:31], v[168:169]
	v_pk_add_f32 v[32:33], v[32:33], v[170:171]
	v_pk_add_f32 v[26:27], v[26:27], v[172:173]
	v_pk_add_f32 v[28:29], v[28:29], v[174:175]
	v_pk_add_f32 v[22:23], v[22:23], v[176:177]
	v_pk_add_f32 v[24:25], v[24:25], v[178:179]
	v_pk_add_f32 v[18:19], v[18:19], v[182:183]
	v_pk_add_f32 v[20:21], v[20:21], v[184:185]
	s_add_u32 vcc_lo, s2, 0xa0000
	s_addc_u32 vcc_hi, s3, 0
	global_store_dwordx4 v142, v[30:33], vcc
	global_store_dwordx4 v142, v[26:29], vcc offset:16
	global_store_dwordx4 v142, v[22:25], vcc offset:512
	global_store_dwordx4 v142, v[18:21], vcc offset:528
	v_mul_f32_e32 v202, v30, v30
	v_fmac_f32_e32 v202, v31, v31
	v_fmac_f32_e32 v202, v32, v32
	v_fmac_f32_e32 v202, v33, v33
	v_mul_f32_e32 v203, v26, v26
	v_fmac_f32_e32 v203, v27, v27
	v_fmac_f32_e32 v203, v28, v28
	v_fmac_f32_e32 v203, v29, v29
	v_mul_f32_e32 v204, v22, v22
	v_fmac_f32_e32 v204, v23, v23
	v_fmac_f32_e32 v204, v24, v24
	v_fmac_f32_e32 v204, v25, v25
	v_mul_f32_e32 v205, v18, v18
	v_fmac_f32_e32 v205, v19, v19
	v_fmac_f32_e32 v205, v20, v20
	v_fmac_f32_e32 v205, v21, v21
	v_add_f32_e32 v202, v202, v203
	v_add_f32_e32 v204, v204, v205
	v_add_f32_e32 v202, v202, v204
	ds_bpermute_b32 v206, v253, v202
	s_add_u32 vcc_lo, s12, 0x50000
	s_addc_u32 vcc_hi, s13, 0
	v_pk_mul_f32 v[30:31], v[30:31], v[152:153]
	v_pk_mul_f32 v[32:33], v[32:33], v[154:155]
	v_pk_mul_f32 v[26:27], v[26:27], v[156:157]
	v_pk_mul_f32 v[28:29], v[28:29], v[158:159]
	v_cvt_pk_bf16_f32 v30, v30, v31
	v_cvt_pk_bf16_f32 v31, v32, v33
	v_cvt_pk_bf16_f32 v32, v26, v27
	v_cvt_pk_bf16_f32 v33, v28, v29
	global_store_dwordx4 v143, v[30:33], vcc
	v_pk_mul_f32 v[22:23], v[22:23], v[160:161]
	v_pk_mul_f32 v[24:25], v[24:25], v[162:163]
	v_pk_mul_f32 v[18:19], v[18:19], v[164:165]
	v_pk_mul_f32 v[20:21], v[20:21], v[166:167]
	v_cvt_pk_bf16_f32 v22, v22, v23
	v_cvt_pk_bf16_f32 v23, v24, v25
	v_cvt_pk_bf16_f32 v24, v18, v19
	v_cvt_pk_bf16_f32 v25, v20, v21
	global_store_dwordx4 v143, v[22:25], vcc offset:256
	s_waitcnt lgkmcnt(0)
	v_add_f32_e32 v202, v202, v206
	ds_bpermute_b32 v206, v230, v202
	s_waitcnt lgkmcnt(0)
	v_add_f32_e32 v202, v202, v206
	s_and_saveexec_b64 s[28:29], s[6:7]
	global_atomic_add_f32 v146, v202, s[16:17] offset:640
	s_or_b64 exec, exec, s[28:29]
	s_waitcnt vmcnt(10)
	v_pk_add_f32 v[14:15], v[14:15], v[186:187]
	v_pk_add_f32 v[16:17], v[16:17], v[188:189]
	v_pk_add_f32 v[10:11], v[10:11], v[190:191]
	v_pk_add_f32 v[12:13], v[12:13], v[192:193]
	v_pk_add_f32 v[6:7], v[6:7], v[194:195]
	v_pk_add_f32 v[8:9], v[8:9], v[196:197]
	v_pk_add_f32 v[2:3], v[2:3], v[198:199]
	v_pk_add_f32 v[4:5], v[4:5], v[200:201]
	s_add_u32 vcc_lo, s2, 0xb0000
	s_addc_u32 vcc_hi, s3, 0
	global_store_dwordx4 v142, v[14:17], vcc
	global_store_dwordx4 v142, v[10:13], vcc offset:16
	global_store_dwordx4 v142, v[6:9], vcc offset:512
	global_store_dwordx4 v142, v[2:5], vcc offset:528
	v_mul_f32_e32 v202, v14, v14
	v_fmac_f32_e32 v202, v15, v15
	v_fmac_f32_e32 v202, v16, v16
	v_fmac_f32_e32 v202, v17, v17
	v_mul_f32_e32 v203, v10, v10
	v_fmac_f32_e32 v203, v11, v11
	v_fmac_f32_e32 v203, v12, v12
	v_fmac_f32_e32 v203, v13, v13
	v_mul_f32_e32 v204, v6, v6
	v_fmac_f32_e32 v204, v7, v7
	v_fmac_f32_e32 v204, v8, v8
	v_fmac_f32_e32 v204, v9, v9
	v_mul_f32_e32 v205, v2, v2
	v_fmac_f32_e32 v205, v3, v3
	v_fmac_f32_e32 v205, v4, v4
	v_fmac_f32_e32 v205, v5, v5
	v_add_f32_e32 v202, v202, v203
	v_add_f32_e32 v204, v204, v205
	v_add_f32_e32 v202, v202, v204
	ds_bpermute_b32 v206, v253, v202
	s_add_u32 vcc_lo, s12, 0x58000
	s_addc_u32 vcc_hi, s13, 0
	v_pk_mul_f32 v[14:15], v[14:15], v[152:153]
	v_pk_mul_f32 v[16:17], v[16:17], v[154:155]
	v_pk_mul_f32 v[10:11], v[10:11], v[156:157]
	v_pk_mul_f32 v[12:13], v[12:13], v[158:159]
	v_cvt_pk_bf16_f32 v14, v14, v15
	v_cvt_pk_bf16_f32 v15, v16, v17
	v_cvt_pk_bf16_f32 v16, v10, v11
	v_cvt_pk_bf16_f32 v17, v12, v13
	global_store_dwordx4 v143, v[14:17], vcc
	v_pk_mul_f32 v[6:7], v[6:7], v[160:161]
	v_pk_mul_f32 v[8:9], v[8:9], v[162:163]
	v_pk_mul_f32 v[2:3], v[2:3], v[164:165]
	v_pk_mul_f32 v[4:5], v[4:5], v[166:167]
	v_cvt_pk_bf16_f32 v6, v6, v7
	v_cvt_pk_bf16_f32 v7, v8, v9
	v_cvt_pk_bf16_f32 v8, v2, v3
	v_cvt_pk_bf16_f32 v9, v4, v5
	global_store_dwordx4 v143, v[6:9], vcc offset:256
	s_waitcnt lgkmcnt(0)
	v_add_f32_e32 v202, v202, v206
	ds_bpermute_b32 v206, v230, v202
	s_waitcnt lgkmcnt(0)
	v_add_f32_e32 v202, v202, v206
	s_and_saveexec_b64 s[28:29], s[6:7]
	global_atomic_add_f32 v146, v202, s[16:17] offset:704
	s_or_b64 exec, exec, s[28:29]
	s_andn2_b64 vcc, exec, s[8:9]
	s_mov_b64 s[8:9], -1
	s_cbranch_vccnz .LBB0_1043
	s_andn2_b64 vcc, exec, s[10:11]
	s_cbranch_vccnz .LBB0_1042
	s_barrier
	s_branch .LBB0_1042
